# residual-GEMM epilogue de-serialised: residual tiles of two row groups fetched together, later groups one group ahead, no load waits behind stores/atomics
# speedup vs baseline: 1.0283x; 1.0016x over previous
; __device__ __forceinline__ unsigned cvt_pk_bf16(float lo, float hi) { unsigned r; asm volatile("v_cvt_pk_bf16_f32 %0, %1, %2" : "=v"(r) : "v"(lo), "v"(hi)); return r; }
;     __device__ __forceinline__ void operator()(const f32x4 (&acc)[2][2][4][2], const Unit& u, int wr, int wc, int fr_in, int fq_in) const {
;     ...
;                 for (int bj = 0; bj < 2; ++bj) { const size_t o = (size_t)(row0 + ai * HALF + (2 * mh + mm) * 16) * 1024 + colb + bj * HALF;
;                     if constexpr (FIRST) { xv[mm][bj][0] = *(const f32x4*)(xin + o); xv[mm][bj][1] = *(const f32x4*)(xin + o + 4); }
;                     else { const u32x4 w = *(const u32x4*)(xb + o);
;                         xv[mm][bj][0] = (f32x4){__uint_as_float(w.x << 16), __uint_as_float(w.x & 0xffff0000u), __uint_as_float(w.y << 16), __uint_as_float(w.y & 0xffff0000u)};
;                         xv[mm][bj][1] = (f32x4){__uint_as_float(w.z << 16), __uint_as_float(w.z & 0xffff0000u), __uint_as_float(w.w << 16), __uint_as_float(w.w & 0xffff0000u)}; } }
; #pragma unroll
;             for (int mm = 0; mm < 2; ++mm) asm volatile("" : "+v"(xv[mm][0][0]), "+v"(xv[mm][0][1]), "+v"(xv[mm][1][0]), "+v"(xv[mm][1][1]));
; #pragma unroll
;             for (int mm = 0; mm < 2; ++mm) { const int m = 2 * mh + mm; const int row = row0 + ai * HALF + m * 16; float ss = 0.f;
; #pragma unroll
;                 for (int bj = 0; bj < 2; ++bj) {
;                     const f32x4 v0 = xv[mm][bj][0] + acc[ai][bj][m][0] * alpha, v1 = xv[mm][bj][1] + acc[ai][bj][m][1] * alpha;
;                     ss += (v0[0] * v0[0] + v0[1] * v0[1]) + (v0[2] * v0[2] + v0[3] * v0[3]) + (v1[0] * v1[0] + v1[1] * v1[1]) + (v1[2] * v1[2] + v1[3] * v1[3]);
;                     u32x4 w; w.x = cvt_pk_bf16(v0[0], v0[1]); w.y = cvt_pk_bf16(v0[2], v0[3]); w.z = cvt_pk_bf16(v1[0], v1[1]); w.w = cvt_pk_bf16(v1[2], v1[3]);
;                     *(u32x4*)(xb + (size_t)row * 1024 + colb + bj * HALF) = w; }
;                 ss += __shfl_xor(ss, 16); ss += __shfl_xor(ss, 32);
;                 if (fq == 0) __hip_atomic_fetch_add(rowss_next + row, ss, __ATOMIC_RELAXED, __HIP_MEMORY_SCOPE_AGENT); } }
.LBB0_522:
	s_lshl_b32 s6, s58, 8
	v_mov_b32_e32 v132, v169
	v_mov_b32_e32 v133, v168
	s_add_i32 s6, s6, s88
	v_mov_b32_e32 v153, v152
	v_add_u32_e32 v162, s6, v132
	s_lshl_b32 s6, s42, 8
	s_or_b32 s6, s6, s90
	v_lshl_add_u32 v160, v133, 3, s6
	v_ashrrev_i32_e32 v161, 31, v160
	v_lshlrev_b64 v[188:189], 1, v[160:161]
	v_ashrrev_i32_e32 v163, 31, v162
	v_lshl_add_u64 v[164:165], s[94:95], 0, v[188:189]
	v_lshlrev_b64 v[190:191], 11, v[162:163]
	v_lshl_add_u64 v[136:137], v[164:165], 0, v[190:191]
	v_cmp_eq_u32_e32 vcc, 0, v133
	v_lshlrev_b32_e32 v220, 11, v162
	v_lshl_add_u32 v220, v160, 1, v220
	global_load_dwordx4 v[192:195], v220, s[94:95]
	global_load_dwordx4 v[208:211], v220, s[94:95] offset:256
	v_add_u32_e32 v221, 0x8000, v220
	global_load_dwordx4 v[230:233], v221, s[94:95]
	global_load_dwordx4 v[234:237], v221, s[94:95] offset:256
	v_add_u32_e32 v221, 0x10000, v220
	global_load_dwordx4 v[238:241], v221, s[94:95]
	global_load_dwordx4 v[242:245], v221, s[94:95] offset:256
	v_add_u32_e32 v221, 0x18000, v220
	global_load_dwordx4 v[246:249], v221, s[94:95]
	global_load_dwordx4 v[250:253], v221, s[94:95] offset:256
	s_waitcnt vmcnt(4)
	v_mov_b32_e32 v132, v192
	v_mov_b32_e32 v133, v193
	v_mov_b32_e32 v134, v194
	v_mov_b32_e32 v135, v195
	v_lshlrev_b32_e32 v172, 16, v132
	v_and_b32_e32 v173, 0xffff0000, v132
	v_lshlrev_b32_e32 v174, 16, v133
	v_and_b32_e32 v175, 0xffff0000, v133
	v_lshlrev_b32_e32 v176, 16, v134
	v_and_b32_e32 v177, 0xffff0000, v134
	v_lshlrev_b32_e32 v178, 16, v135
	v_and_b32_e32 v179, 0xffff0000, v135
	v_mov_b32_e32 v132, v208
	v_mov_b32_e32 v133, v209
	v_mov_b32_e32 v134, v210
	v_mov_b32_e32 v135, v211
	v_lshlrev_b32_e32 v180, 16, v132
	v_and_b32_e32 v181, 0xffff0000, v132
	v_add_u32_e32 v132, 16, v162
	v_lshlrev_b32_e32 v182, 16, v133
	v_and_b32_e32 v183, 0xffff0000, v133
	v_ashrrev_i32_e32 v133, 31, v132
	v_lshlrev_b64 v[166:167], 11, v[132:133]
	v_lshl_add_u64 v[140:141], v[164:165], 0, v[166:167]
	v_lshlrev_b32_e32 v184, 16, v134
	v_and_b32_e32 v185, 0xffff0000, v134
	v_lshlrev_b32_e32 v186, 16, v135
	v_and_b32_e32 v187, 0xffff0000, v135
	v_mov_b32_e32 v132, v230
	v_mov_b32_e32 v133, v231
	v_mov_b32_e32 v134, v232
	v_mov_b32_e32 v135, v233
	v_lshlrev_b32_e32 v136, 16, v132
	v_mov_b32_e32 v140, v234
	v_mov_b32_e32 v141, v235
	v_mov_b32_e32 v142, v236
	v_mov_b32_e32 v143, v237
	v_and_b32_e32 v137, 0xffff0000, v132
	v_pk_fma_f32 v[130:131], v[152:153], v[130:131], v[174:175]
	v_pk_fma_f32 v[128:129], v[154:155], v[128:129], v[172:173]
	v_pk_fma_f32 v[172:173], v[152:153], v[126:127], v[178:179]
	v_pk_fma_f32 v[126:127], v[154:155], v[124:125], v[176:177]
	v_mul_f32_e32 v124, v129, v129
	v_mul_f32_e32 v125, v131, v131
	v_fmac_f32_e32 v124, v128, v128
	v_fmac_f32_e32 v125, v130, v130
	v_add_f32_e32 v124, v124, v125
	v_mul_f32_e32 v125, v127, v127
	v_fmac_f32_e32 v125, v126, v126
	v_add_f32_e32 v124, v125, v124
	v_mul_f32_e32 v125, v173, v173
	v_lshlrev_b32_e32 v138, 16, v133
	v_and_b32_e32 v139, 0xffff0000, v133
	v_lshlrev_b32_e32 v132, 16, v134
	v_and_b32_e32 v133, 0xffff0000, v134
	v_lshlrev_b32_e32 v134, 16, v135
	v_and_b32_e32 v135, 0xffff0000, v135
	v_fmac_f32_e32 v125, v172, v172
	v_add_f32_e32 v174, v125, v124
	v_pk_fma_f32 v[122:123], v[152:153], v[122:123], v[182:183]
	v_pk_fma_f32 v[120:121], v[154:155], v[120:121], v[180:181]
	v_lshlrev_b32_e32 v144, 16, v140
	v_and_b32_e32 v145, 0xffff0000, v140
	v_lshlrev_b32_e32 v146, 16, v141
	v_and_b32_e32 v147, 0xffff0000, v141
	v_lshlrev_b32_e32 v140, 16, v142
	v_and_b32_e32 v141, 0xffff0000, v142
	v_lshlrev_b32_e32 v142, 16, v143
	v_and_b32_e32 v143, 0xffff0000, v143
	v_cvt_pk_bf16_f32 v124, v128, v129
	v_lshl_add_u64 v[128:129], s[94:95], 0, v[190:191]
	v_cvt_pk_bf16_f32 v125, v130, v131
	v_cvt_pk_bf16_f32 v126, v126, v127
	v_cvt_pk_bf16_f32 v127, v172, v173
	v_lshl_add_u64 v[128:129], v[128:129], 0, v[188:189]
	global_store_dwordx4 v[128:129], v[124:127], off
	s_nop 1
	v_pk_fma_f32 v[126:127], v[154:155], v[116:117], v[184:185]
	v_mul_f32_e32 v116, v121, v121
	v_mul_f32_e32 v117, v123, v123
	v_fmac_f32_e32 v116, v120, v120
	v_fmac_f32_e32 v117, v122, v122
	v_add_f32_e32 v116, v116, v117
	v_mul_f32_e32 v117, v127, v127
	v_pk_fma_f32 v[124:125], v[152:153], v[118:119], v[186:187]
	v_fmac_f32_e32 v117, v126, v126
	v_add_f32_e32 v116, v117, v116
	v_mul_f32_e32 v117, v125, v125
	v_cvt_pk_bf16_f32 v118, v120, v121
	v_fmac_f32_e32 v117, v124, v124
	v_cvt_pk_bf16_f32 v119, v122, v123
	v_cvt_pk_bf16_f32 v120, v126, v127
	v_cvt_pk_bf16_f32 v121, v124, v125
	global_store_dwordx4 v[128:129], v[118:121], off offset:256
	v_add_f32_e32 v116, v117, v116
	v_xor_b32_e32 v117, 16, v219
	v_and_b32_e32 v118, 64, v219
	v_add_u32_e32 v119, 64, v118
	v_cmp_lt_i32_e64 s[42:43], v117, v119
	v_add_f32_e32 v116, v174, v116
	s_nop 0
	v_cndmask_b32_e64 v117, v219, v117, s[42:43]
	v_lshlrev_b32_e32 v120, 2, v117
	ds_bpermute_b32 v117, v120, v116
	s_waitcnt lgkmcnt(0)
	v_add_f32_e32 v118, v116, v117
	v_xor_b32_e32 v116, 32, v219
	v_cmp_lt_i32_e64 s[42:43], v116, v119
	s_nop 1
	v_cndmask_b32_e64 v116, v219, v116, s[42:43]
	v_lshlrev_b32_e32 v121, 2, v116
	ds_bpermute_b32 v119, v121, v118
	v_lshl_add_u64 v[116:117], v[162:163], 2, s[46:47]
	s_and_saveexec_b64 s[42:43], vcc
	s_cbranch_execz .LBB0_524
	s_waitcnt lgkmcnt(0)
	v_add_f32_e32 v118, v118, v119
	global_atomic_add_f32 v[116:117], v118, off

; __device__ __forceinline__ unsigned cvt_pk_bf16(float lo, float hi) { unsigned r; asm volatile("v_cvt_pk_bf16_f32 %0, %1, %2" : "=v"(r) : "v"(lo), "v"(hi)); return r; }
;     __device__ __forceinline__ void operator()(const f32x4 (&acc)[2][2][4][2], const Unit& u, int wr, int wc, int fr_in, int fq_in) const {
;     ...
;                 for (int bj = 0; bj < 2; ++bj) { const size_t o = (size_t)(row0 + ai * HALF + (2 * mh + mm) * 16) * 1024 + colb + bj * HALF;
;                     if constexpr (FIRST) { xv[mm][bj][0] = *(const f32x4*)(xin + o); xv[mm][bj][1] = *(const f32x4*)(xin + o + 4); }
;                     else { const u32x4 w = *(const u32x4*)(xb + o);
;                         xv[mm][bj][0] = (f32x4){__uint_as_float(w.x << 16), __uint_as_float(w.x & 0xffff0000u), __uint_as_float(w.y << 16), __uint_as_float(w.y & 0xffff0000u)};
;                         xv[mm][bj][1] = (f32x4){__uint_as_float(w.z << 16), __uint_as_float(w.z & 0xffff0000u), __uint_as_float(w.w << 16), __uint_as_float(w.w & 0xffff0000u)}; } }
; #pragma unroll
;             for (int mm = 0; mm < 2; ++mm) asm volatile("" : "+v"(xv[mm][0][0]), "+v"(xv[mm][0][1]), "+v"(xv[mm][1][0]), "+v"(xv[mm][1][1]));
; #pragma unroll
;             for (int mm = 0; mm < 2; ++mm) { const int m = 2 * mh + mm; const int row = row0 + ai * HALF + m * 16; float ss = 0.f;
; #pragma unroll
;                 for (int bj = 0; bj < 2; ++bj) {
;                     const f32x4 v0 = xv[mm][bj][0] + acc[ai][bj][m][0] * alpha, v1 = xv[mm][bj][1] + acc[ai][bj][m][1] * alpha;
;                     ss += (v0[0] * v0[0] + v0[1] * v0[1]) + (v0[2] * v0[2] + v0[3] * v0[3]) + (v1[0] * v1[0] + v1[1] * v1[1]) + (v1[2] * v1[2] + v1[3] * v1[3]);
;                     u32x4 w; w.x = cvt_pk_bf16(v0[0], v0[1]); w.y = cvt_pk_bf16(v0[2], v0[3]); w.z = cvt_pk_bf16(v1[0], v1[1]); w.w = cvt_pk_bf16(v1[2], v1[3]);
;                     *(u32x4*)(xb + (size_t)row * 1024 + colb + bj * HALF) = w; }
;                 ss += __shfl_xor(ss, 16); ss += __shfl_xor(ss, 32);
;                 if (fq == 0) __hip_atomic_fetch_add(rowss_next + row, ss, __ATOMIC_RELAXED, __HIP_MEMORY_SCOPE_AGENT); } }
.LBB0_526:
	s_or_b64 exec, exec, s[42:43]
	v_add_u32_e32 v100, 32, v162
	s_waitcnt lgkmcnt(0)
	v_ashrrev_i32_e32 v101, 31, v100
	v_add_u32_e32 v108, 48, v162
	v_lshlrev_b64 v[142:143], 11, v[100:101]
	v_ashrrev_i32_e32 v109, 31, v108
	v_lshl_add_u64 v[104:105], v[164:165], 0, v[142:143]
	v_lshlrev_b64 v[118:119], 11, v[108:109]
	v_add_u32_e32 v221, 0x40000, v220
	global_load_dwordx4 v[192:195], v221, s[94:95]
	global_load_dwordx4 v[208:211], v221, s[94:95] offset:256
	v_add_u32_e32 v221, 0x48000, v220
	global_load_dwordx4 v[230:233], v221, s[94:95]
	global_load_dwordx4 v[234:237], v221, s[94:95] offset:256
	s_waitcnt vmcnt(10)
	v_mov_b32_e32 v100, v238
	v_mov_b32_e32 v101, v239
	v_mov_b32_e32 v102, v240
	v_mov_b32_e32 v103, v241
	v_mov_b32_e32 v104, v242
	v_mov_b32_e32 v105, v243
	v_mov_b32_e32 v106, v244
	v_mov_b32_e32 v107, v245
	v_lshl_add_u64 v[112:113], v[164:165], 0, v[118:119]
	v_mov_b32_e32 v108, v246
	v_mov_b32_e32 v109, v247
	v_mov_b32_e32 v110, v248
	v_mov_b32_e32 v111, v249
	v_mov_b32_e32 v122, v250
	v_mov_b32_e32 v123, v251
	v_mov_b32_e32 v124, v252
	v_mov_b32_e32 v125, v253
	v_mov_b32_e32 v153, v152
	v_lshlrev_b32_e32 v126, 16, v100
	v_and_b32_e32 v127, 0xffff0000, v100
	v_lshlrev_b32_e32 v128, 16, v101
	v_and_b32_e32 v129, 0xffff0000, v101
	v_lshlrev_b32_e32 v130, 16, v102
	v_and_b32_e32 v131, 0xffff0000, v102
	v_lshlrev_b32_e32 v132, 16, v103
	v_and_b32_e32 v133, 0xffff0000, v103
	v_lshlrev_b32_e32 v134, 16, v104
	v_and_b32_e32 v135, 0xffff0000, v104
	v_lshlrev_b32_e32 v136, 16, v105
	v_and_b32_e32 v137, 0xffff0000, v105
	v_lshlrev_b32_e32 v138, 16, v106
	v_and_b32_e32 v139, 0xffff0000, v106
	v_lshlrev_b32_e32 v140, 16, v107
	v_and_b32_e32 v141, 0xffff0000, v107
	v_lshlrev_b32_e32 v112, 16, v108
	v_and_b32_e32 v113, 0xffff0000, v108
	v_lshlrev_b32_e32 v114, 16, v109
	v_and_b32_e32 v115, 0xffff0000, v109
	v_lshlrev_b32_e32 v108, 16, v110
	v_and_b32_e32 v109, 0xffff0000, v110
	v_lshlrev_b32_e32 v110, 16, v111
	v_and_b32_e32 v111, 0xffff0000, v111
	v_lshlrev_b32_e32 v104, 16, v122
	v_and_b32_e32 v105, 0xffff0000, v122
	v_lshlrev_b32_e32 v106, 16, v123
	v_and_b32_e32 v107, 0xffff0000, v123
	v_lshlrev_b32_e32 v100, 16, v124
	v_and_b32_e32 v101, 0xffff0000, v124
	v_lshlrev_b32_e32 v102, 16, v125
	v_and_b32_e32 v103, 0xffff0000, v125
	s_nop 0
	v_pk_fma_f32 v[98:99], v[152:153], v[98:99], v[128:129]
	v_pk_fma_f32 v[96:97], v[154:155], v[96:97], v[126:127]
	v_pk_fma_f32 v[94:95], v[152:153], v[94:95], v[132:133]
	v_pk_fma_f32 v[92:93], v[154:155], v[92:93], v[130:131]
	v_pk_fma_f32 v[90:91], v[152:153], v[90:91], v[136:137]
	v_pk_fma_f32 v[88:89], v[154:155], v[88:89], v[134:135]
	v_pk_fma_f32 v[122:123], v[152:153], v[86:87], v[140:141]
	v_pk_fma_f32 v[124:125], v[154:155], v[84:85], v[138:139]
	v_mul_f32_e32 v126, v97, v97
	v_mul_f32_e32 v127, v99, v99
	v_mul_f32_e32 v128, v93, v93
	v_mul_f32_e32 v129, v95, v95
	v_cvt_pk_bf16_f32 v84, v96, v97
	v_cvt_pk_bf16_f32 v85, v98, v99
	v_cvt_pk_bf16_f32 v86, v92, v93
	v_cvt_pk_bf16_f32 v87, v94, v95
	v_mul_f32_e32 v93, v89, v89
	v_mul_f32_e32 v95, v91, v91
	v_mul_f32_e32 v97, v125, v125
	v_fmac_f32_e32 v126, v96, v96
	v_fmac_f32_e32 v127, v98, v98
	v_fmac_f32_e32 v93, v88, v88
	v_fmac_f32_e32 v95, v90, v90
	v_mul_f32_e32 v99, v123, v123
	v_fmac_f32_e32 v128, v92, v92
	v_fmac_f32_e32 v97, v124, v124
	v_add_f32_e32 v92, v126, v127
	v_add_f32_e32 v93, v93, v95
	v_fmac_f32_e32 v129, v94, v94
	v_fmac_f32_e32 v99, v122, v122
	v_add_f32_e32 v92, v128, v92
	v_add_f32_e32 v93, v97, v93
	v_add_f32_e32 v92, v129, v92
	v_add_f32_e32 v93, v99, v93
	v_add_f32_e32 v94, v92, v93
	ds_bpermute_b32 v95, v120, v94
	v_lshl_add_u64 v[92:93], s[94:95], 0, v[142:143]
	v_lshl_add_u64 v[92:93], v[160:161], 1, v[92:93]
	global_store_dwordx4 v[92:93], v[84:87], off
	s_waitcnt lgkmcnt(0)
	s_nop 0
	v_add_f32_e32 v84, v94, v95
	ds_bpermute_b32 v85, v121, v84
	v_cvt_pk_bf16_f32 v86, v88, v89
	v_cvt_pk_bf16_f32 v87, v90, v91
	v_cvt_pk_bf16_f32 v88, v124, v125
	v_cvt_pk_bf16_f32 v89, v122, v123
	global_store_dwordx4 v[92:93], v[86:89], off offset:256
	s_and_saveexec_b64 s[42:43], vcc
	s_cbranch_execz .LBB0_528
	s_waitcnt lgkmcnt(0)
	v_add_f32_e32 v84, v84, v85
	global_atomic_add_f32 v[116:117], v84, off offset:128

; __device__ __forceinline__ unsigned cvt_pk_bf16(float lo, float hi) { unsigned r; asm volatile("v_cvt_pk_bf16_f32 %0, %1, %2" : "=v"(r) : "v"(lo), "v"(hi)); return r; }
;     __device__ __forceinline__ void operator()(const f32x4 (&acc)[2][2][4][2], const Unit& u, int wr, int wc, int fr_in, int fq_in) const {
;     ...
;                 for (int bj = 0; bj < 2; ++bj) { const size_t o = (size_t)(row0 + ai * HALF + (2 * mh + mm) * 16) * 1024 + colb + bj * HALF;
;                     if constexpr (FIRST) { xv[mm][bj][0] = *(const f32x4*)(xin + o); xv[mm][bj][1] = *(const f32x4*)(xin + o + 4); }
;                     else { const u32x4 w = *(const u32x4*)(xb + o);
;                         xv[mm][bj][0] = (f32x4){__uint_as_float(w.x << 16), __uint_as_float(w.x & 0xffff0000u), __uint_as_float(w.y << 16), __uint_as_float(w.y & 0xffff0000u)};
;                         xv[mm][bj][1] = (f32x4){__uint_as_float(w.z << 16), __uint_as_float(w.z & 0xffff0000u), __uint_as_float(w.w << 16), __uint_as_float(w.w & 0xffff0000u)}; } }
; #pragma unroll
;             for (int mm = 0; mm < 2; ++mm) asm volatile("" : "+v"(xv[mm][0][0]), "+v"(xv[mm][0][1]), "+v"(xv[mm][1][0]), "+v"(xv[mm][1][1]));
; #pragma unroll
;             for (int mm = 0; mm < 2; ++mm) { const int m = 2 * mh + mm; const int row = row0 + ai * HALF + m * 16; float ss = 0.f;
; #pragma unroll
;                 for (int bj = 0; bj < 2; ++bj) {
;                     const f32x4 v0 = xv[mm][bj][0] + acc[ai][bj][m][0] * alpha, v1 = xv[mm][bj][1] + acc[ai][bj][m][1] * alpha;
;                     ss += (v0[0] * v0[0] + v0[1] * v0[1]) + (v0[2] * v0[2] + v0[3] * v0[3]) + (v1[0] * v1[0] + v1[1] * v1[1]) + (v1[2] * v1[2] + v1[3] * v1[3]);
;                     u32x4 w; w.x = cvt_pk_bf16(v0[0], v0[1]); w.y = cvt_pk_bf16(v0[2], v0[3]); w.z = cvt_pk_bf16(v1[0], v1[1]); w.w = cvt_pk_bf16(v1[2], v1[3]);
;                     *(u32x4*)(xb + (size_t)row * 1024 + colb + bj * HALF) = w; }
;                 ss += __shfl_xor(ss, 16); ss += __shfl_xor(ss, 32);
;                 if (fq == 0) __hip_atomic_fetch_add(rowss_next + row, ss, __ATOMIC_RELAXED, __HIP_MEMORY_SCOPE_AGENT); } }
.LBB0_530:
	s_or_b64 exec, exec, s[42:43]
	v_add_u32_e32 v68, 0x80, v162
	s_waitcnt lgkmcnt(0)
	v_ashrrev_i32_e32 v69, 31, v68
	v_add_u32_e32 v76, 0x90, v162
	v_lshlrev_b64 v[106:107], 11, v[68:69]
	v_ashrrev_i32_e32 v77, 31, v76
	v_lshl_add_u64 v[72:73], v[164:165], 0, v[106:107]
	v_lshlrev_b64 v[84:85], 11, v[76:77]
	v_add_u32_e32 v221, 0x50000, v220
	global_load_dwordx4 v[238:241], v221, s[94:95]
	global_load_dwordx4 v[242:245], v221, s[94:95] offset:256
	v_add_u32_e32 v221, 0x58000, v220
	global_load_dwordx4 v[246:249], v221, s[94:95]
	global_load_dwordx4 v[250:253], v221, s[94:95] offset:256
	s_waitcnt vmcnt(10)
	v_mov_b32_e32 v68, v192
	v_mov_b32_e32 v69, v193
	v_mov_b32_e32 v70, v194
	v_mov_b32_e32 v71, v195
	v_mov_b32_e32 v72, v208
	v_mov_b32_e32 v73, v209
	v_mov_b32_e32 v74, v210
	v_mov_b32_e32 v75, v211
	v_lshl_add_u64 v[80:81], v[164:165], 0, v[84:85]
	v_mov_b32_e32 v76, v230
	v_mov_b32_e32 v77, v231
	v_mov_b32_e32 v78, v232
	v_mov_b32_e32 v79, v233
	v_mov_b32_e32 v86, v234
	v_mov_b32_e32 v87, v235
	v_mov_b32_e32 v88, v236
	v_mov_b32_e32 v89, v237
	v_mov_b32_e32 v153, v152
	v_lshlrev_b32_e32 v90, 16, v68
	v_and_b32_e32 v91, 0xffff0000, v68
	v_lshlrev_b32_e32 v92, 16, v69
	v_and_b32_e32 v93, 0xffff0000, v69
	v_lshlrev_b32_e32 v94, 16, v70
	v_and_b32_e32 v95, 0xffff0000, v70
	v_lshlrev_b32_e32 v96, 16, v71
	v_and_b32_e32 v97, 0xffff0000, v71
	v_lshlrev_b32_e32 v98, 16, v72
	v_and_b32_e32 v99, 0xffff0000, v72
	v_lshlrev_b32_e32 v100, 16, v73
	v_and_b32_e32 v101, 0xffff0000, v73
	v_lshlrev_b32_e32 v102, 16, v74
	v_and_b32_e32 v103, 0xffff0000, v74
	v_lshlrev_b32_e32 v104, 16, v75
	v_and_b32_e32 v105, 0xffff0000, v75
	v_lshlrev_b32_e32 v80, 16, v76
	v_and_b32_e32 v81, 0xffff0000, v76
	v_lshlrev_b32_e32 v82, 16, v77
	v_and_b32_e32 v83, 0xffff0000, v77
	v_lshlrev_b32_e32 v76, 16, v78
	v_and_b32_e32 v77, 0xffff0000, v78
	v_lshlrev_b32_e32 v78, 16, v79
	v_and_b32_e32 v79, 0xffff0000, v79
	v_lshlrev_b32_e32 v72, 16, v86
	v_and_b32_e32 v73, 0xffff0000, v86
	v_lshlrev_b32_e32 v74, 16, v87
	v_and_b32_e32 v75, 0xffff0000, v87
	v_lshlrev_b32_e32 v68, 16, v88
	v_and_b32_e32 v69, 0xffff0000, v88
	v_lshlrev_b32_e32 v70, 16, v89
	v_and_b32_e32 v71, 0xffff0000, v89
	s_nop 0
	v_pk_fma_f32 v[66:67], v[152:153], v[66:67], v[92:93]
	v_pk_fma_f32 v[64:65], v[154:155], v[64:65], v[90:91]
	v_pk_fma_f32 v[62:63], v[152:153], v[62:63], v[96:97]
	v_pk_fma_f32 v[60:61], v[154:155], v[60:61], v[94:95]
	v_pk_fma_f32 v[58:59], v[152:153], v[58:59], v[100:101]
	v_pk_fma_f32 v[56:57], v[154:155], v[56:57], v[98:99]
	v_pk_fma_f32 v[86:87], v[152:153], v[54:55], v[104:105]
	v_pk_fma_f32 v[88:89], v[154:155], v[52:53], v[102:103]
	v_mul_f32_e32 v90, v65, v65
	v_mul_f32_e32 v91, v67, v67
	v_mul_f32_e32 v92, v61, v61
	v_mul_f32_e32 v93, v63, v63
	v_cvt_pk_bf16_f32 v52, v64, v65
	v_cvt_pk_bf16_f32 v53, v66, v67
	v_cvt_pk_bf16_f32 v54, v60, v61
	v_cvt_pk_bf16_f32 v55, v62, v63
	v_mul_f32_e32 v61, v57, v57
	v_mul_f32_e32 v63, v59, v59
	v_mul_f32_e32 v65, v89, v89
	v_fmac_f32_e32 v90, v64, v64
	v_fmac_f32_e32 v91, v66, v66
	v_fmac_f32_e32 v61, v56, v56
	v_fmac_f32_e32 v63, v58, v58
	v_mul_f32_e32 v67, v87, v87
	v_fmac_f32_e32 v92, v60, v60
	v_fmac_f32_e32 v65, v88, v88
	v_add_f32_e32 v60, v90, v91
	v_add_f32_e32 v61, v61, v63
	v_fmac_f32_e32 v93, v62, v62
	v_fmac_f32_e32 v67, v86, v86
	v_add_f32_e32 v60, v92, v60
	v_add_f32_e32 v61, v65, v61
	v_add_f32_e32 v60, v93, v60
	v_add_f32_e32 v61, v67, v61
	v_add_f32_e32 v62, v60, v61
	ds_bpermute_b32 v63, v120, v62
	v_lshl_add_u64 v[60:61], s[94:95], 0, v[106:107]
	v_lshl_add_u64 v[60:61], v[160:161], 1, v[60:61]
	global_store_dwordx4 v[60:61], v[52:55], off
	s_waitcnt lgkmcnt(0)
	s_nop 0
	v_add_f32_e32 v52, v62, v63
	ds_bpermute_b32 v53, v121, v52
	v_cvt_pk_bf16_f32 v54, v56, v57
	v_cvt_pk_bf16_f32 v55, v58, v59
	v_cvt_pk_bf16_f32 v56, v88, v89
	v_cvt_pk_bf16_f32 v57, v86, v87
	global_store_dwordx4 v[60:61], v[54:57], off offset:256
	s_and_saveexec_b64 s[42:43], vcc
	s_cbranch_execz .LBB0_532
	s_waitcnt lgkmcnt(0)
	v_add_f32_e32 v52, v52, v53
	global_atomic_add_f32 v[116:117], v52, off offset:512

; __device__ __forceinline__ unsigned cvt_pk_bf16(float lo, float hi) { unsigned r; asm volatile("v_cvt_pk_bf16_f32 %0, %1, %2" : "=v"(r) : "v"(lo), "v"(hi)); return r; }
;     __device__ __forceinline__ void operator()(const f32x4 (&acc)[2][2][4][2], const Unit& u, int wr, int wc, int fr_in, int fq_in) const {
;     ...
;                 for (int bj = 0; bj < 2; ++bj) { const size_t o = (size_t)(row0 + ai * HALF + (2 * mh + mm) * 16) * 1024 + colb + bj * HALF;
;                     if constexpr (FIRST) { xv[mm][bj][0] = *(const f32x4*)(xin + o); xv[mm][bj][1] = *(const f32x4*)(xin + o + 4); }
;                     else { const u32x4 w = *(const u32x4*)(xb + o);
;                         xv[mm][bj][0] = (f32x4){__uint_as_float(w.x << 16), __uint_as_float(w.x & 0xffff0000u), __uint_as_float(w.y << 16), __uint_as_float(w.y & 0xffff0000u)};
;                         xv[mm][bj][1] = (f32x4){__uint_as_float(w.z << 16), __uint_as_float(w.z & 0xffff0000u), __uint_as_float(w.w << 16), __uint_as_float(w.w & 0xffff0000u)}; } }
; #pragma unroll
;             for (int mm = 0; mm < 2; ++mm) asm volatile("" : "+v"(xv[mm][0][0]), "+v"(xv[mm][0][1]), "+v"(xv[mm][1][0]), "+v"(xv[mm][1][1]));
; #pragma unroll
;             for (int mm = 0; mm < 2; ++mm) { const int m = 2 * mh + mm; const int row = row0 + ai * HALF + m * 16; float ss = 0.f;
; #pragma unroll
;                 for (int bj = 0; bj < 2; ++bj) {
;                     const f32x4 v0 = xv[mm][bj][0] + acc[ai][bj][m][0] * alpha, v1 = xv[mm][bj][1] + acc[ai][bj][m][1] * alpha;
;                     ss += (v0[0] * v0[0] + v0[1] * v0[1]) + (v0[2] * v0[2] + v0[3] * v0[3]) + (v1[0] * v1[0] + v1[1] * v1[1]) + (v1[2] * v1[2] + v1[3] * v1[3]);
;                     u32x4 w; w.x = cvt_pk_bf16(v0[0], v0[1]); w.y = cvt_pk_bf16(v0[2], v0[3]); w.z = cvt_pk_bf16(v1[0], v1[1]); w.w = cvt_pk_bf16(v1[2], v1[3]);
;                     *(u32x4*)(xb + (size_t)row * 1024 + colb + bj * HALF) = w; }
;                 ss += __shfl_xor(ss, 16); ss += __shfl_xor(ss, 32);
;                 if (fq == 0) __hip_atomic_fetch_add(rowss_next + row, ss, __ATOMIC_RELAXED, __HIP_MEMORY_SCOPE_AGENT); } }
.LBB0_534:
	s_or_b64 exec, exec, s[42:43]
	v_add_u32_e32 v36, 0xa0, v162
	s_waitcnt lgkmcnt(0)
	v_ashrrev_i32_e32 v37, 31, v36
	v_add_u32_e32 v44, 0xb0, v162
	v_lshlrev_b64 v[74:75], 11, v[36:37]
	v_ashrrev_i32_e32 v45, 31, v44
	v_lshl_add_u64 v[40:41], v[164:165], 0, v[74:75]
	v_lshlrev_b64 v[52:53], 11, v[44:45]
	s_waitcnt vmcnt(6)
	v_mov_b32_e32 v36, v238
	v_mov_b32_e32 v37, v239
	v_mov_b32_e32 v38, v240
	v_mov_b32_e32 v39, v241
	v_mov_b32_e32 v40, v242
	v_mov_b32_e32 v41, v243
	v_mov_b32_e32 v42, v244
	v_mov_b32_e32 v43, v245
	v_lshl_add_u64 v[48:49], v[164:165], 0, v[52:53]
	v_mov_b32_e32 v44, v246
	v_mov_b32_e32 v45, v247
	v_mov_b32_e32 v46, v248
	v_mov_b32_e32 v47, v249
	v_mov_b32_e32 v54, v250
	v_mov_b32_e32 v55, v251
	v_mov_b32_e32 v56, v252
	v_mov_b32_e32 v57, v253
	v_mov_b32_e32 v153, v152
	v_lshlrev_b32_e32 v58, 16, v36
	v_and_b32_e32 v59, 0xffff0000, v36
	v_lshlrev_b32_e32 v60, 16, v37
	v_and_b32_e32 v61, 0xffff0000, v37
	v_lshlrev_b32_e32 v62, 16, v38
	v_and_b32_e32 v63, 0xffff0000, v38
	v_lshlrev_b32_e32 v64, 16, v39
	v_and_b32_e32 v65, 0xffff0000, v39
	v_lshlrev_b32_e32 v66, 16, v40
	v_and_b32_e32 v67, 0xffff0000, v40
	v_lshlrev_b32_e32 v68, 16, v41
	v_and_b32_e32 v69, 0xffff0000, v41
	v_lshlrev_b32_e32 v70, 16, v42
	v_and_b32_e32 v71, 0xffff0000, v42
	v_lshlrev_b32_e32 v72, 16, v43
	v_and_b32_e32 v73, 0xffff0000, v43
	v_lshlrev_b32_e32 v48, 16, v44
	v_and_b32_e32 v49, 0xffff0000, v44
	v_lshlrev_b32_e32 v50, 16, v45
	v_and_b32_e32 v51, 0xffff0000, v45
	v_lshlrev_b32_e32 v44, 16, v46
	v_and_b32_e32 v45, 0xffff0000, v46
	v_lshlrev_b32_e32 v46, 16, v47
	v_and_b32_e32 v47, 0xffff0000, v47
	v_lshlrev_b32_e32 v40, 16, v54
	v_and_b32_e32 v41, 0xffff0000, v54
	v_lshlrev_b32_e32 v42, 16, v55
	v_and_b32_e32 v43, 0xffff0000, v55
	v_lshlrev_b32_e32 v36, 16, v56
	v_and_b32_e32 v37, 0xffff0000, v56
	v_lshlrev_b32_e32 v38, 16, v57
	v_and_b32_e32 v39, 0xffff0000, v57
	s_nop 0
	v_pk_fma_f32 v[34:35], v[152:153], v[34:35], v[60:61]
	v_pk_fma_f32 v[32:33], v[154:155], v[32:33], v[58:59]
	v_pk_fma_f32 v[30:31], v[152:153], v[30:31], v[64:65]
	v_pk_fma_f32 v[28:29], v[154:155], v[28:29], v[62:63]
	v_pk_fma_f32 v[26:27], v[152:153], v[26:27], v[68:69]
	v_pk_fma_f32 v[24:25], v[154:155], v[24:25], v[66:67]
	v_pk_fma_f32 v[54:55], v[152:153], v[22:23], v[72:73]
	v_pk_fma_f32 v[56:57], v[154:155], v[20:21], v[70:71]
	v_mul_f32_e32 v58, v33, v33
	v_mul_f32_e32 v59, v35, v35
	v_mul_f32_e32 v60, v29, v29
	v_mul_f32_e32 v61, v31, v31
	v_cvt_pk_bf16_f32 v20, v32, v33
	v_cvt_pk_bf16_f32 v21, v34, v35
	v_cvt_pk_bf16_f32 v22, v28, v29
	v_cvt_pk_bf16_f32 v23, v30, v31
	v_mul_f32_e32 v29, v25, v25
	v_mul_f32_e32 v31, v27, v27
	v_mul_f32_e32 v33, v57, v57
	v_fmac_f32_e32 v58, v32, v32
	v_fmac_f32_e32 v59, v34, v34
	v_fmac_f32_e32 v29, v24, v24
	v_fmac_f32_e32 v31, v26, v26
	v_mul_f32_e32 v35, v55, v55
	v_fmac_f32_e32 v60, v28, v28
	v_fmac_f32_e32 v33, v56, v56
	v_add_f32_e32 v28, v58, v59
	v_add_f32_e32 v29, v29, v31
	v_fmac_f32_e32 v61, v30, v30
	v_fmac_f32_e32 v35, v54, v54
	v_add_f32_e32 v28, v60, v28
	v_add_f32_e32 v29, v33, v29
	v_add_f32_e32 v28, v61, v28
	v_add_f32_e32 v29, v35, v29
	v_add_f32_e32 v30, v28, v29
	ds_bpermute_b32 v31, v120, v30
	v_lshl_add_u64 v[28:29], s[94:95], 0, v[74:75]
	v_lshl_add_u64 v[28:29], v[160:161], 1, v[28:29]
	global_store_dwordx4 v[28:29], v[20:23], off
	s_waitcnt lgkmcnt(0)
	s_nop 0
	v_add_f32_e32 v20, v30, v31
	ds_bpermute_b32 v21, v121, v20
	v_cvt_pk_bf16_f32 v22, v24, v25
	v_cvt_pk_bf16_f32 v23, v26, v27
	v_cvt_pk_bf16_f32 v24, v56, v57
	v_cvt_pk_bf16_f32 v25, v54, v55
	global_store_dwordx4 v[28:29], v[22:25], off offset:256
	s_and_saveexec_b64 s[42:43], vcc
	s_cbranch_execz .LBB0_536
	s_waitcnt lgkmcnt(0)
	v_add_f32_e32 v20, v20, v21
	global_atomic_add_f32 v[116:117], v20, off offset:640
